# K-loop start waits in phases B and F no longer drain the previous tile's epilogue stores
# baseline (speedup 1.0000x reference)
; __device__ __forceinline__ int lane_fresh() { int l; asm volatile("v_mbcnt_lo_u32_b32 %0, -1, 0\n\tv_mbcnt_hi_u32_b32 %0, -1, %0" : "=v"(l)); return l; }
; #define WAIT_V(n) asm volatile("s_waitcnt vmcnt(" #n ")" ::: "memory")
; #define WAIT_L(n) asm volatile("s_waitcnt lgkmcnt(" #n ")" ::: "memory")
; #define BAR __builtin_amdgcn_s_barrier()
; template <int PART  , bool SYNC_FIRST = true>
; __device__ __forceinline__ void kloop_t(const u16* __restrict__ A, int lda, const u16* __restrict__ Bt, int ldb, int K, Acc& acc, const int wv) {
;     ...
;   const int wid = wv, lane = lane_fresh(), ktid = wv * 64 + lane, wr = wid >> 2, wc = wid & 3, fr = lane & 15, fq = lane >> 4;
;   bf16x8 At[4][2], B0[2][2], B1[2][2];
;   const int nt = K / BK;
;   unsigned oA0, oA1, oB0, oB1;
;   { int r_, c_; stage_rc(ktid * 16, r_, c_); oA0 = (unsigned)(r_ * lda + c_) * 2u; oB0 = (unsigned)(r_ * ldb + c_) * 2u;
;     stage_rc(ktid * 16 + 8192, r_, c_); oA1 = (unsigned)(r_ * lda + c_) * 2u; oB1 = (unsigned)(r_ * ldb + c_) * 2u; }
;   if (PART != 2) {
;     if (SYNC_FIRST) { WAIT_V(0); WAIT_L(0); __syncthreads(); }
;     STAGE(SB(0, 0), Bt, ldb, 0, 0); STAGE(SA(0, 0), A, lda, 0, 0);
;     STAGE(SB(0, 1), Bt, ldb, HALF, 0); STAGE(SA(0, 1), A, lda, HALF, 0);
;   }
;   if (PART == 1) return;
;   if (wr == 1) BAR;
;   WAIT_V(4); BAR;
;   STAGE(SB(1, 0), Bt, ldb, 0, 1); STAGE(SA(1, 0), A, lda, 0, 1); STAGE(SB(1, 1), Bt, ldb, HALF, 1);
;   WAIT_V(6); BAR;
.LBB0_192:
	v_lshl_add_u32 v140, v0, 4, s29
	v_ashrrev_i32_e32 v2, 31, v140
	v_lshrrev_b32_e32 v2, 22, v2
	v_add_u32_e32 v2, v140, v2
	v_ashrrev_i32_e32 v2, 10, v2
	v_mul_i32_i24_e32 v3, 0x400, v2
	v_sub_u32_e32 v3, v140, v3
	v_lshrrev_b32_e32 v4, 4, v3
	v_bitop3_b32 v3, v4, v3, 32 bitop3:0x6c
	v_ashrrev_i32_e32 v5, 31, v3
	v_lshrrev_b32_e32 v5, 26, v5
	v_add_u32_e32 v5, v3, v5
	v_lshrrev_b32_e32 v6, 6, v5
	v_and_b32_e32 v5, 0xc0, v5
	v_lshlrev_b32_e32 v4, 3, v2
	v_lshlrev_b32_e32 v2, 5, v2
	v_sub_u32_e32 v3, v3, v5
	v_and_b32_e32 v4, 0x1ffff0, v4
	v_and_b32_e32 v2, 32, v2
	v_ashrrev_i16_sdwa v3, v136, sext(v3) dst_sel:DWORD dst_unused:UNUSED_PAD src0_sel:DWORD src1_sel:BYTE_0
	v_add_u32_sdwa v2, v2, sext(v3) dst_sel:DWORD dst_unused:UNUSED_PAD src0_sel:DWORD src1_sel:WORD_0
	v_add_lshl_u32 v3, v6, v4, 11
	v_lshl_add_u32 v139, v2, 1, v3
	v_add_u32_e32 v2, 0x2000, v140
	v_ashrrev_i32_e32 v3, 31, v2
	v_lshrrev_b32_e32 v3, 22, v3
	v_add_u32_e32 v3, v2, v3
	v_ashrrev_i32_e32 v3, 10, v3
	v_mul_i32_i24_e32 v4, 0x400, v3
	v_sub_u32_e32 v2, v2, v4
	v_lshrrev_b32_e32 v4, 4, v2
	v_bitop3_b32 v2, v4, v2, 32 bitop3:0x6c
	v_ashrrev_i32_e32 v5, 31, v2
	s_add_i32 s4, s78, 0xfffff900
	v_lshrrev_b32_e32 v5, 26, v5
	s_cmpk_gt_i32 s78, 0x6ff
	v_add_u32_e32 v5, v2, v5
	s_cselect_b32 s4, s4, s78
	v_lshrrev_b32_e32 v6, 6, v5
	v_and_b32_e32 v5, 0xffc0, v5
	s_lshl_b32 s5, s4, 8
	v_sub_u32_e32 v2, v2, v5
	s_and_b32 s33, s5, 0x3f00
	s_lshl_b32 s52, s4, 2
	v_lshrrev_b16_e32 v5, 7, v2
	s_and_b32 s38, s52, 0xffffff00
	s_lshl_b32 s4, s33, 11
	v_and_b32_e32 v5, 1, v5
	s_add_u32 s4, s48, s4
	v_lshlrev_b32_e32 v4, 3, v3
	v_lshlrev_b32_e32 v3, 5, v3
	v_add_u16_e32 v2, v2, v5
	s_addc_u32 s5, s49, 0
	s_ashr_i32 s39, s38, 31
	v_and_b32_e32 v4, 0x1ffff0, v4
	v_and_b32_e32 v3, 32, v3
	v_ashrrev_i16_sdwa v2, v136, sext(v2) dst_sel:DWORD dst_unused:UNUSED_PAD src0_sel:DWORD src1_sel:BYTE_0
	s_lshl_b64 s[36:37], s[38:39], 11
	v_add_u32_sdwa v2, v3, sext(v2) dst_sel:DWORD dst_unused:UNUSED_PAD src0_sel:DWORD src1_sel:WORD_0
	v_add_lshl_u32 v3, v6, v4, 11
	s_add_u32 s36, s50, s36
	v_lshl_add_u32 v141, v2, 1, v3
	s_addc_u32 s37, s51, s37
	v_mov_b32_e32 v128, v139
	v_mov_b32_e32 v2, v141
	v_add_u32_e32 v142, s68, v140
	v_readlane_b32 s39, v251, 0
	s_nop 3
	s_cmp_eq_u32 s78, s39
	s_cbranch_scc1 .Lkw_b0_first
	s_waitcnt vmcnt(20)
	s_branch .Lkw_b0_join
.Lkw_b0_first:
	s_waitcnt vmcnt(4)
.Lkw_b0_join:
	s_barrier
	v_readfirstlane_b32 s39, v142
	v_lshl_add_u64 v[4:5], s[36:37], 0, v[128:129]
	v_mov_b32_e32 v3, v129
	v_add_u32_e32 v143, 0x2000, v142
	v_lshl_add_u64 v[4:5], v[4:5], 0, s[12:13]
	s_mov_b32 m0, s39
	v_lshl_add_u64 v[2:3], s[36:37], 0, v[2:3]
	v_readfirstlane_b32 s39, v143
	global_load_lds_dwordx4 v[4:5], off
	v_lshl_add_u64 v[2:3], v[2:3], 0, s[12:13]
	s_mov_b32 m0, s39
	v_add_u32_e32 v144, 16, v140
	global_load_lds_dwordx4 v[2:3], off
	v_mov_b32_e32 v128, v139
	v_mov_b32_e32 v2, v141
	v_add_u32_e32 v145, 0x8000, v144
	v_mov_b32_e32 v3, v129
	v_lshl_add_u64 v[4:5], s[4:5], 0, v[128:129]
	v_readfirstlane_b32 s39, v145
	v_add_u32_e32 v146, 0xa000, v144
	v_lshl_add_u64 v[4:5], v[4:5], 0, s[12:13]
	s_mov_b32 m0, s39
	v_lshl_add_u64 v[2:3], s[4:5], 0, v[2:3]
	v_readfirstlane_b32 s39, v146
	v_add_u32_e32 v147, s69, v140
	global_load_lds_dwordx4 v[4:5], off
	v_lshl_add_u64 v[2:3], v[2:3], 0, s[12:13]
	s_mov_b32 m0, s39
	s_add_u32 s40, s36, 0x40080
	v_readfirstlane_b32 s39, v147
	v_add_u32_e32 v148, 0x2000, v147
	global_load_lds_dwordx4 v[2:3], off
	s_addc_u32 s41, s37, 0
	v_mov_b32_e32 v2, v141
	v_mov_b32_e32 v3, v139
	s_mov_b32 m0, s39
	v_readfirstlane_b32 s39, v148
	v_and_b32_e32 v1, 15, v0
	global_load_lds_dwordx4 v3, s[40:41]
	s_mov_b32 m0, s39
	v_lshlrev_b32_e32 v5, 2, v0
	global_load_lds_dwordx4 v2, s[40:41]
	v_lshlrev_b32_e32 v3, 6, v1
	v_and_b32_e32 v4, 48, v0
	v_and_b32_e32 v5, 32, v5
	v_bitop3_b32 v3, v3, v5, v4 bitop3:0x36
	v_ashrrev_i32_e32 v2, 1, v0
	v_add_u32_e32 v149, s31, v3
	v_add_u32_e32 v150, s35, v3
	v_add_u32_e32 v151, s68, v3
	v_add_u32_e32 v152, s69, v3
	v_or_b32_e32 v3, s57, v1
	v_or_b32_e32 v7, s60, v1
	v_or_b32_e32 v10, s62, v1
	v_or_b32_e32 v1, s64, v1
	v_add_u32_e32 v2, 32, v2
	v_lshlrev_b32_e32 v5, 6, v3
	v_lshlrev_b32_e32 v3, 2, v3
	v_lshlrev_b32_e32 v8, 6, v7
	v_lshlrev_b32_e32 v7, 2, v7
	v_lshlrev_b32_e32 v11, 6, v10
	v_lshlrev_b32_e32 v10, 2, v10
	v_lshlrev_b32_e32 v13, 6, v1
	v_lshlrev_b32_e32 v1, 2, v1
	v_readlane_b32 s39, v251, 0
	s_nop 3
	s_cmp_eq_u32 s78, s39
	s_cbranch_scc1 .Lkw_b1_first
	s_waitcnt vmcnt(22)
	s_branch .Lkw_b1_join
; #define WAIT_V(n) asm volatile("s_waitcnt vmcnt(" #n ")" ::: "memory")
; #define BAR __builtin_amdgcn_s_barrier()
; template <int PART  , bool SYNC_FIRST = true>
; __device__ __forceinline__ void kloop_t(const u16* __restrict__ A, int lda, const u16* __restrict__ Bt, int ldb, int K, Acc& acc, const int wv) {
;     ...
;   WAIT_V(4); BAR;
;   STAGE(SB(1, 0), Bt, ldb, 0, 1); STAGE(SA(1, 0), A, lda, 0, 1); STAGE(SB(1, 1), Bt, ldb, HALF, 1);
;   WAIT_V(6); BAR;
.Lkw_b1_first:
	s_waitcnt vmcnt(6)
.Lkw_b1_join:
	v_ashrrev_i32_e32 v0, 6, v0
	v_ashrrev_i32_e32 v2, 5, v2
	v_and_or_b32 v5, v5, s70, v4
	v_and_b32_e32 v3, 32, v3
	v_and_or_b32 v8, v8, s70, v4
	v_and_b32_e32 v7, 32, v7
	v_and_or_b32 v11, v11, s70, v4
	v_and_b32_e32 v10, 32, v10
	v_and_or_b32 v4, v13, s70, v4
	v_and_b32_e32 v1, 32, v1
	v_add_lshl_u32 v153, v0, s56, 10
	v_add_lshl_u32 v154, v2, s56, 10
	v_add_lshl_u32 v155, v0, s58, 10
	v_add_lshl_u32 v156, v2, s58, 10
	v_xad_u32 v3, v5, v3, 16
	v_add_lshl_u32 v5, v0, s59, 10
	v_add_lshl_u32 v6, v2, s59, 10
	v_xad_u32 v7, v8, v7, 16
	v_add_lshl_u32 v8, v0, s61, 10
	v_add_lshl_u32 v9, v2, s61, 10
	v_xad_u32 v10, v11, v10, 16
	v_add_lshl_u32 v11, v0, s63, 10
	v_add_lshl_u32 v12, v2, s63, 10
	v_xad_u32 v1, v4, v1, 16
	v_add_lshl_u32 v4, v0, s65, 10
	v_add_lshl_u32 v2, v2, s65, 10
	v_mov_b32_e32 v0, 0
	s_mov_b32 s39, -2
	s_mov_b64 s[40:41], 0
	v_add_u32_e32 v130, v3, v5
	v_add_u32_e32 v131, v3, v6
	v_add_u32_e32 v132, v7, v8
	v_add_u32_e32 v133, v7, v9
	v_add_u32_e32 v134, v10, v11
	v_add_u32_e32 v135, v10, v12
	v_add_u32_e32 v137, v1, v4
	v_add_u32_e32 v138, v1, v2
	v_mov_b32_e32 v1, v0
	v_mov_b32_e32 v2, v0
	v_mov_b32_e32 v3, v0
	v_mov_b32_e32 v4, v0
	v_mov_b32_e32 v5, v0
	v_mov_b32_e32 v6, v0
	v_mov_b32_e32 v7, v0
	v_mov_b32_e32 v8, v0
	v_mov_b32_e32 v9, v0
	v_mov_b32_e32 v10, v0
	v_mov_b32_e32 v11, v0
	v_mov_b32_e32 v12, v0
	v_mov_b32_e32 v13, v0
	v_mov_b32_e32 v14, v0
	v_mov_b32_e32 v15, v0
	v_mov_b32_e32 v16, v0
	v_mov_b32_e32 v17, v0
	v_mov_b32_e32 v18, v0
	v_mov_b32_e32 v19, v0
	v_mov_b32_e32 v20, v0
	v_mov_b32_e32 v21, v0
	v_mov_b32_e32 v22, v0
	v_mov_b32_e32 v23, v0
	v_mov_b32_e32 v24, v0
	v_mov_b32_e32 v25, v0
	v_mov_b32_e32 v26, v0
	v_mov_b32_e32 v27, v0
	v_mov_b32_e32 v28, v0
	v_mov_b32_e32 v29, v0
	v_mov_b32_e32 v30, v0
	v_mov_b32_e32 v31, v0
	v_mov_b32_e32 v32, v0
	v_mov_b32_e32 v33, v0
	v_mov_b32_e32 v34, v0
	v_mov_b32_e32 v35, v0
	v_mov_b32_e32 v36, v0
	v_mov_b32_e32 v37, v0
	v_mov_b32_e32 v38, v0
	v_mov_b32_e32 v39, v0
	v_mov_b32_e32 v40, v0
	v_mov_b32_e32 v41, v0
	v_mov_b32_e32 v42, v0
	v_mov_b32_e32 v43, v0
	v_mov_b32_e32 v44, v0
	v_mov_b32_e32 v45, v0
	v_mov_b32_e32 v46, v0
	v_mov_b32_e32 v47, v0
	v_mov_b32_e32 v48, v0
	v_mov_b32_e32 v49, v0
	v_mov_b32_e32 v50, v0
	v_mov_b32_e32 v51, v0
	v_mov_b32_e32 v52, v0
	v_mov_b32_e32 v53, v0
	v_mov_b32_e32 v54, v0
	v_mov_b32_e32 v55, v0
	v_mov_b32_e32 v56, v0
	v_mov_b32_e32 v57, v0
	v_mov_b32_e32 v58, v0
	v_mov_b32_e32 v59, v0
	v_mov_b32_e32 v60, v0
	v_mov_b32_e32 v61, v0
	v_mov_b32_e32 v62, v0
	v_mov_b32_e32 v63, v0
	v_mov_b32_e32 v64, v0
	v_mov_b32_e32 v65, v0
	v_mov_b32_e32 v66, v0
	v_mov_b32_e32 v67, v0
	v_mov_b32_e32 v68, v0
	v_mov_b32_e32 v69, v0
	v_mov_b32_e32 v70, v0
	v_mov_b32_e32 v71, v0
	v_mov_b32_e32 v72, v0
	v_mov_b32_e32 v73, v0
	v_mov_b32_e32 v74, v0
	v_mov_b32_e32 v75, v0
	v_mov_b32_e32 v76, v0
	v_mov_b32_e32 v77, v0
	v_mov_b32_e32 v78, v0
	v_mov_b32_e32 v79, v0
	v_mov_b32_e32 v80, v0
	v_mov_b32_e32 v81, v0
	v_mov_b32_e32 v82, v0
	v_mov_b32_e32 v83, v0
	v_mov_b32_e32 v84, v0
	v_mov_b32_e32 v85, v0
	v_mov_b32_e32 v86, v0
	v_mov_b32_e32 v87, v0
	v_mov_b32_e32 v88, v0
	v_mov_b32_e32 v89, v0
	v_mov_b32_e32 v90, v0
	v_mov_b32_e32 v91, v0
	v_mov_b32_e32 v92, v0
	v_mov_b32_e32 v93, v0
	v_mov_b32_e32 v94, v0
	v_mov_b32_e32 v95, v0
	v_mov_b32_e32 v96, v0
	v_mov_b32_e32 v97, v0
	v_mov_b32_e32 v98, v0
	v_mov_b32_e32 v99, v0
	v_mov_b32_e32 v100, v0
	v_mov_b32_e32 v101, v0
	v_mov_b32_e32 v102, v0
	v_mov_b32_e32 v103, v0
	v_mov_b32_e32 v104, v0
	v_mov_b32_e32 v105, v0
	v_mov_b32_e32 v106, v0
	v_mov_b32_e32 v107, v0
	v_mov_b32_e32 v108, v0
	v_mov_b32_e32 v109, v0
	v_mov_b32_e32 v110, v0
	v_mov_b32_e32 v111, v0
	v_mov_b32_e32 v112, v0
	v_mov_b32_e32 v113, v0
	v_mov_b32_e32 v114, v0
	v_mov_b32_e32 v115, v0
	v_mov_b32_e32 v116, v0
	v_mov_b32_e32 v117, v0
	v_mov_b32_e32 v118, v0
	v_mov_b32_e32 v119, v0
	v_mov_b32_e32 v120, v0
	v_mov_b32_e32 v121, v0
	v_mov_b32_e32 v122, v0
	v_mov_b32_e32 v123, v0
	v_mov_b32_e32 v124, v0
	v_mov_b32_e32 v125, v0
	v_mov_b32_e32 v126, v0
	v_mov_b32_e32 v127, v0
	s_barrier

; __device__ __forceinline__ int lane_fresh() { int l; asm volatile("v_mbcnt_lo_u32_b32 %0, -1, 0\n\tv_mbcnt_hi_u32_b32 %0, -1, %0" : "=v"(l)); return l; }
; #define WAIT_V(n) asm volatile("s_waitcnt vmcnt(" #n ")" ::: "memory")
; #define WAIT_L(n) asm volatile("s_waitcnt lgkmcnt(" #n ")" ::: "memory")
; #define BAR __builtin_amdgcn_s_barrier()
; template <int PART  , bool SYNC_FIRST = true>
; __device__ __forceinline__ void kloop_t(const u16* __restrict__ A, int lda, const u16* __restrict__ Bt, int ldb, int K, Acc& acc, const int wv) {
;     ...
;   const int wid = wv, lane = lane_fresh(), ktid = wv * 64 + lane, wr = wid >> 2, wc = wid & 3, fr = lane & 15, fq = lane >> 4;
;   bf16x8 At[4][2], B0[2][2], B1[2][2];
;   const int nt = K / BK;
;   unsigned oA0, oA1, oB0, oB1;
;   { int r_, c_; stage_rc(ktid * 16, r_, c_); oA0 = (unsigned)(r_ * lda + c_) * 2u; oB0 = (unsigned)(r_ * ldb + c_) * 2u;
;     stage_rc(ktid * 16 + 8192, r_, c_); oA1 = (unsigned)(r_ * lda + c_) * 2u; oB1 = (unsigned)(r_ * ldb + c_) * 2u; }
;   if (PART != 2) {
;     if (SYNC_FIRST) { WAIT_V(0); WAIT_L(0); __syncthreads(); }
;     STAGE(SB(0, 0), Bt, ldb, 0, 0); STAGE(SA(0, 0), A, lda, 0, 0);
;     STAGE(SB(0, 1), Bt, ldb, HALF, 0); STAGE(SA(0, 1), A, lda, HALF, 0);
;   }
;   if (PART == 1) return;
;   if (wr == 1) BAR;
;   WAIT_V(4); BAR;
.LBB0_1068:
	v_lshl_add_u32 v141, v0, 4, s53
	v_ashrrev_i32_e32 v2, 31, v141
	v_lshrrev_b32_e32 v2, 22, v2
	v_add_u32_e32 v2, v141, v2
	v_ashrrev_i32_e32 v2, 10, v2
	v_mul_i32_i24_e32 v3, 0x400, v2
	v_sub_u32_e32 v3, v141, v3
	v_lshrrev_b32_e32 v4, 4, v3
	v_bitop3_b32 v3, v4, v3, 32 bitop3:0x6c
	v_ashrrev_i32_e32 v5, 31, v3
	v_lshrrev_b32_e32 v5, 26, v5
	v_add_u32_e32 v5, v3, v5
	v_lshrrev_b32_e32 v6, 6, v5
	v_and_b32_e32 v5, 0xc0, v5
	v_lshlrev_b32_e32 v4, 3, v2
	v_lshlrev_b32_e32 v2, 5, v2
	v_sub_u32_e32 v3, v3, v5
	v_and_b32_e32 v4, 0x1ffff0, v4
	v_and_b32_e32 v2, 32, v2
	v_ashrrev_i16_sdwa v3, v132, sext(v3) dst_sel:DWORD dst_unused:UNUSED_PAD src0_sel:DWORD src1_sel:BYTE_0
	v_add_u32_sdwa v2, v2, sext(v3) dst_sel:DWORD dst_unused:UNUSED_PAD src0_sel:DWORD src1_sel:WORD_0
	v_add_lshl_u32 v3, v6, v4, 11
	v_lshl_add_u32 v140, v2, 1, v3
	v_add_u32_e32 v2, 0x2000, v141
	v_ashrrev_i32_e32 v3, 31, v2
	v_lshrrev_b32_e32 v3, 22, v3
	v_add_u32_e32 v3, v2, v3
	v_ashrrev_i32_e32 v3, 10, v3
	v_mul_i32_i24_e32 v4, 0x400, v3
	v_sub_u32_e32 v2, v2, v4
	v_lshrrev_b32_e32 v4, 4, v2
	v_bitop3_b32 v2, v4, v2, 32 bitop3:0x6c
	v_ashrrev_i32_e32 v5, 31, v2
	v_lshrrev_b32_e32 v5, 26, v5
	v_add_u32_e32 v5, v2, v5
	s_lshl_b32 s36, s67, 11
	v_lshrrev_b32_e32 v6, 6, v5
	v_and_b32_e32 v5, 0xffc0, v5
	s_and_b32 s79, s36, 0x1f80000
	s_lshl_b32 s36, s69, 11
	v_sub_u32_e32 v2, v2, v5
	s_and_b32 s80, s36, 0x780000
	s_lshl_b32 s36, s75, 8
	v_lshrrev_b16_e32 v5, 7, v2
	s_lshl_b32 s37, s75, 2
	s_and_b32 s77, s36, 0x3f00
	v_and_b32_e32 v5, 1, v5
	s_and_b32 s78, s37, 0xf00
	s_lshl_b32 s36, s77, 11
	v_lshlrev_b32_e32 v4, 3, v3
	v_lshlrev_b32_e32 v3, 5, v3
	v_add_u16_e32 v2, v2, v5
	s_add_u32 s36, s8, s36
	v_and_b32_e32 v4, 0x1ffff0, v4
	v_and_b32_e32 v3, 32, v3
	v_ashrrev_i16_sdwa v2, v132, sext(v2) dst_sel:DWORD dst_unused:UNUSED_PAD src0_sel:DWORD src1_sel:BYTE_0
	s_addc_u32 s37, s9, 0
	s_lshl_b32 s38, s78, 11
	v_add_u32_sdwa v2, v3, sext(v2) dst_sel:DWORD dst_unused:UNUSED_PAD src0_sel:DWORD src1_sel:WORD_0
	v_add_lshl_u32 v3, v6, v4, 11
	s_add_u32 s38, s33, s38
	v_lshl_add_u32 v142, v2, 1, v3
	s_addc_u32 s39, s44, 0
	v_mov_b32_e32 v128, v140
	v_mov_b32_e32 v2, v142
	v_add_u32_e32 v143, s71, v141
	v_readlane_b32 s40, v251, 0
	s_nop 3
	s_cmp_eq_u32 s75, s40
	s_cbranch_scc1 .Lkw_f0_first
	s_waitcnt vmcnt(20)
	s_branch .Lkw_f0_join

; #define WAIT_V(n) asm volatile("s_waitcnt vmcnt(" #n ")" ::: "memory")
; #define BAR __builtin_amdgcn_s_barrier()
; template <int PART  , bool SYNC_FIRST = true>
; __device__ __forceinline__ void kloop_t(const u16* __restrict__ A, int lda, const u16* __restrict__ Bt, int ldb, int K, Acc& acc, const int wv) {
;     ...
;   WAIT_V(4); BAR;
;   STAGE(SB(1, 0), Bt, ldb, 0, 1); STAGE(SA(1, 0), A, lda, 0, 1); STAGE(SB(1, 1), Bt, ldb, HALF, 1);
;   WAIT_V(6); BAR;
.Lkw_f0_join:
	s_barrier
	v_readfirstlane_b32 s40, v143
	v_lshl_add_u64 v[4:5], s[38:39], 0, v[128:129]
	v_mov_b32_e32 v3, v129
	v_add_u32_e32 v144, 0x2000, v143
	v_lshl_add_u64 v[4:5], v[4:5], 0, s[16:17]
	s_mov_b32 m0, s40
	v_lshl_add_u64 v[2:3], s[38:39], 0, v[2:3]
	v_readfirstlane_b32 s40, v144
	global_load_lds_dwordx4 v[4:5], off
	v_lshl_add_u64 v[2:3], v[2:3], 0, s[16:17]
	s_mov_b32 m0, s40
	v_add_u32_e32 v145, 16, v141
	global_load_lds_dwordx4 v[2:3], off
	v_mov_b32_e32 v128, v140
	v_mov_b32_e32 v2, v142
	v_add_u32_e32 v146, 0x8000, v145
	v_mov_b32_e32 v3, v129
	v_lshl_add_u64 v[4:5], s[36:37], 0, v[128:129]
	v_readfirstlane_b32 s40, v146
	v_add_u32_e32 v147, 0xa000, v145
	v_lshl_add_u64 v[4:5], v[4:5], 0, s[16:17]
	s_mov_b32 m0, s40
	v_lshl_add_u64 v[2:3], s[36:37], 0, v[2:3]
	v_readfirstlane_b32 s40, v147
	v_add_u32_e32 v148, s72, v141
	global_load_lds_dwordx4 v[4:5], off
	v_lshl_add_u64 v[2:3], v[2:3], 0, s[16:17]
	s_mov_b32 m0, s40
	s_add_u32 s38, s38, 0x40080
	v_readfirstlane_b32 s40, v148
	v_add_u32_e32 v149, 0x2000, v148
	global_load_lds_dwordx4 v[2:3], off
	s_addc_u32 s39, s39, 0
	v_mov_b32_e32 v2, v140
	v_mov_b32_e32 v3, v142
	s_mov_b32 m0, s40
	v_readfirstlane_b32 s40, v149
	v_and_b32_e32 v1, 15, v0
	global_load_lds_dwordx4 v2, s[38:39]
	s_mov_b32 m0, s40
	v_lshlrev_b32_e32 v5, 2, v0
	global_load_lds_dwordx4 v3, s[38:39]
	v_lshlrev_b32_e32 v3, 6, v1
	v_and_b32_e32 v4, 48, v0
	v_and_b32_e32 v5, 32, v5
	v_bitop3_b32 v3, v3, v5, v4 bitop3:0x36
	v_ashrrev_i32_e32 v2, 1, v0
	v_add_u32_e32 v150, s54, v3
	v_add_u32_e32 v151, s55, v3
	v_add_u32_e32 v152, s71, v3
	v_add_u32_e32 v153, s72, v3
	v_or_b32_e32 v3, s57, v1
	v_or_b32_e32 v7, s60, v1
	v_or_b32_e32 v10, s62, v1
	v_or_b32_e32 v1, s64, v1
	v_add_u32_e32 v2, 32, v2
	v_lshlrev_b32_e32 v5, 6, v3
	v_lshlrev_b32_e32 v3, 2, v3
	v_lshlrev_b32_e32 v8, 6, v7
	v_lshlrev_b32_e32 v7, 2, v7
	v_lshlrev_b32_e32 v11, 6, v10
	v_lshlrev_b32_e32 v10, 2, v10
	v_lshlrev_b32_e32 v13, 6, v1
	v_lshlrev_b32_e32 v1, 2, v1
	v_readlane_b32 s40, v251, 0
	s_nop 3
	s_cmp_eq_u32 s75, s40
	s_cbranch_scc1 .Lkw_f1_first
	s_waitcnt vmcnt(22)
	s_branch .Lkw_f1_join

; #define WAIT_V(n) asm volatile("s_waitcnt vmcnt(" #n ")" ::: "memory")
; #define BAR __builtin_amdgcn_s_barrier()
; template <int PART  , bool SYNC_FIRST = true>
; __device__ __forceinline__ void kloop_t(const u16* __restrict__ A, int lda, const u16* __restrict__ Bt, int ldb, int K, Acc& acc, const int wv) {
;     ...
;   WAIT_V(4); BAR;
;   STAGE(SB(1, 0), Bt, ldb, 0, 1); STAGE(SA(1, 0), A, lda, 0, 1); STAGE(SB(1, 1), Bt, ldb, HALF, 1);
;   WAIT_V(6); BAR;
.Lkw_f1_join:
	v_ashrrev_i32_e32 v0, 6, v0
	v_ashrrev_i32_e32 v2, 5, v2
	v_and_or_b32 v5, v5, s73, v4
	v_and_b32_e32 v3, 32, v3
	v_and_or_b32 v8, v8, s73, v4
	v_and_b32_e32 v7, 32, v7
	v_and_or_b32 v11, v11, s73, v4
	v_and_b32_e32 v10, 32, v10
	v_and_or_b32 v4, v13, s73, v4
	v_and_b32_e32 v1, 32, v1
	v_add_lshl_u32 v154, v0, s56, 10
	v_add_lshl_u32 v155, v2, s56, 10
	v_add_lshl_u32 v156, v0, s58, 10
	v_add_lshl_u32 v157, v2, s58, 10
	v_xad_u32 v3, v5, v3, 16
	v_add_lshl_u32 v5, v0, s59, 10
	v_add_lshl_u32 v6, v2, s59, 10
	v_xad_u32 v7, v8, v7, 16
	v_add_lshl_u32 v8, v0, s61, 10
	v_add_lshl_u32 v9, v2, s61, 10
	v_xad_u32 v10, v11, v10, 16
	v_add_lshl_u32 v11, v0, s63, 10
	v_add_lshl_u32 v12, v2, s63, 10
	v_xad_u32 v1, v4, v1, 16
	v_add_lshl_u32 v4, v0, s65, 10
	v_add_lshl_u32 v2, v2, s65, 10
	v_mov_b32_e32 v0, 0
	s_mov_b32 s81, -2
	v_add_u32_e32 v130, v3, v5
	v_add_u32_e32 v131, v3, v6
	v_add_u32_e32 v134, v7, v8
	v_add_u32_e32 v135, v7, v9
	v_add_u32_e32 v136, v10, v11
	v_add_u32_e32 v137, v10, v12
	v_add_u32_e32 v138, v1, v4
	v_add_u32_e32 v139, v1, v2
	s_mov_b64 s[38:39], s[50:51]
	v_mov_b32_e32 v1, v0
	v_mov_b32_e32 v2, v0
	v_mov_b32_e32 v3, v0
	v_mov_b32_e32 v4, v0
	v_mov_b32_e32 v5, v0
	v_mov_b32_e32 v6, v0
	v_mov_b32_e32 v7, v0
	v_mov_b32_e32 v8, v0
	v_mov_b32_e32 v9, v0
	v_mov_b32_e32 v10, v0
	v_mov_b32_e32 v11, v0
	v_mov_b32_e32 v12, v0
	v_mov_b32_e32 v13, v0
	v_mov_b32_e32 v14, v0
	v_mov_b32_e32 v15, v0
	v_mov_b32_e32 v16, v0
	v_mov_b32_e32 v17, v0
	v_mov_b32_e32 v18, v0
	v_mov_b32_e32 v19, v0
	v_mov_b32_e32 v20, v0
	v_mov_b32_e32 v21, v0
	v_mov_b32_e32 v22, v0
	v_mov_b32_e32 v23, v0
	v_mov_b32_e32 v24, v0
	v_mov_b32_e32 v25, v0
	v_mov_b32_e32 v26, v0
	v_mov_b32_e32 v27, v0
	v_mov_b32_e32 v28, v0
	v_mov_b32_e32 v29, v0
	v_mov_b32_e32 v30, v0
	v_mov_b32_e32 v31, v0
	v_mov_b32_e32 v32, v0
	v_mov_b32_e32 v33, v0
	v_mov_b32_e32 v34, v0
	v_mov_b32_e32 v35, v0
	v_mov_b32_e32 v36, v0
	v_mov_b32_e32 v37, v0
	v_mov_b32_e32 v38, v0
	v_mov_b32_e32 v39, v0
	v_mov_b32_e32 v40, v0
	v_mov_b32_e32 v41, v0
	v_mov_b32_e32 v42, v0
	v_mov_b32_e32 v43, v0
	v_mov_b32_e32 v44, v0
	v_mov_b32_e32 v45, v0
	v_mov_b32_e32 v46, v0
	v_mov_b32_e32 v47, v0
	v_mov_b32_e32 v48, v0
	v_mov_b32_e32 v49, v0
	v_mov_b32_e32 v50, v0
	v_mov_b32_e32 v51, v0
	v_mov_b32_e32 v52, v0
	v_mov_b32_e32 v53, v0
	v_mov_b32_e32 v54, v0
	v_mov_b32_e32 v55, v0
	v_mov_b32_e32 v56, v0
	v_mov_b32_e32 v57, v0
	v_mov_b32_e32 v58, v0
	v_mov_b32_e32 v59, v0
	v_mov_b32_e32 v60, v0
	v_mov_b32_e32 v61, v0
	v_mov_b32_e32 v62, v0
	v_mov_b32_e32 v63, v0
	v_mov_b32_e32 v64, v0
	v_mov_b32_e32 v65, v0
	v_mov_b32_e32 v66, v0
	v_mov_b32_e32 v67, v0
	v_mov_b32_e32 v68, v0
	v_mov_b32_e32 v69, v0
	v_mov_b32_e32 v70, v0
	v_mov_b32_e32 v71, v0
	v_mov_b32_e32 v72, v0
	v_mov_b32_e32 v73, v0
	v_mov_b32_e32 v74, v0
	v_mov_b32_e32 v75, v0
	v_mov_b32_e32 v76, v0
	v_mov_b32_e32 v77, v0
	v_mov_b32_e32 v78, v0
	v_mov_b32_e32 v79, v0
	v_mov_b32_e32 v80, v0
	v_mov_b32_e32 v81, v0
	v_mov_b32_e32 v82, v0
	v_mov_b32_e32 v83, v0
	v_mov_b32_e32 v84, v0
	v_mov_b32_e32 v85, v0
	v_mov_b32_e32 v86, v0
	v_mov_b32_e32 v87, v0
	v_mov_b32_e32 v88, v0
	v_mov_b32_e32 v89, v0
	v_mov_b32_e32 v90, v0
	v_mov_b32_e32 v91, v0
	v_mov_b32_e32 v92, v0
	v_mov_b32_e32 v93, v0
	v_mov_b32_e32 v94, v0
	v_mov_b32_e32 v95, v0
	v_mov_b32_e32 v96, v0
	v_mov_b32_e32 v97, v0
	v_mov_b32_e32 v98, v0
	v_mov_b32_e32 v99, v0
	v_mov_b32_e32 v100, v0
	v_mov_b32_e32 v101, v0
	v_mov_b32_e32 v102, v0
	v_mov_b32_e32 v103, v0
	v_mov_b32_e32 v104, v0
	v_mov_b32_e32 v105, v0
	v_mov_b32_e32 v106, v0
	v_mov_b32_e32 v107, v0
	v_mov_b32_e32 v108, v0
	v_mov_b32_e32 v109, v0
	v_mov_b32_e32 v110, v0
	v_mov_b32_e32 v111, v0
	v_mov_b32_e32 v112, v0
	v_mov_b32_e32 v113, v0
	v_mov_b32_e32 v114, v0
	v_mov_b32_e32 v115, v0
	v_mov_b32_e32 v116, v0
	v_mov_b32_e32 v117, v0
	v_mov_b32_e32 v118, v0
	v_mov_b32_e32 v119, v0
	v_mov_b32_e32 v120, v0
	v_mov_b32_e32 v121, v0
	v_mov_b32_e32 v122, v0
	v_mov_b32_e32 v123, v0
	v_mov_b32_e32 v124, v0
	v_mov_b32_e32 v125, v0
	v_mov_b32_e32 v126, v0
	v_mov_b32_e32 v127, v0
	s_barrier
